# attention work queue order: the 64 MoBA qb=1 items moved ahead of the dilated and memory items (longest-first), qb=0 items stay last
# baseline (speedup 1.0000x reference)
.LBB0_265:
	s_barrier
	s_and_saveexec_b64 s[0:1], s[4:5]
	v_mov_b32_e32 v0, s27
	ds_write_b32 v0, v171
	s_or_b64 exec, exec, s[0:1]
	s_waitcnt lgkmcnt(0)
	s_barrier
	ds_read_b32 v0, v173
	s_movk_i32 s0, 0x6ff
	s_waitcnt lgkmcnt(0)
	v_cmp_lt_i32_e32 vcc, s0, v0
	v_readfirstlane_b32 s89, v0
	s_mov_b64 s[0:1], -1
	s_cbranch_vccnz .LBB0_264
	s_cmpk_lt_u32 s89, 0x180
	s_cbranch_scc1 .Lq_remap_done
	s_cmpk_ge_u32 s89, 0x6c0
	s_cbranch_scc1 .Lq_remap_done
	s_cmpk_lt_u32 s89, 0x1c0
	s_cselect_b32 s98, 0x540, 0
	s_add_i32 s89, s89, s98
	s_sub_i32 s89, s89, 64
.Lq_remap_done:
	s_and_saveexec_b64 s[0:1], s[4:5]
	s_cbranch_execz .LBB0_272
	s_mov_b64 s[52:53], exec
	v_mbcnt_lo_u32_b32 v0, s52, 0
	v_mbcnt_hi_u32_b32 v0, s53, v0
	v_cmp_eq_u32_e32 vcc, 0, v0
	s_and_saveexec_b64 s[2:3], vcc
	s_cbranch_execz .LBB0_271
	s_bcnt1_i32_b64 s20, s[52:53]
	v_mov_b32_e32 v2, s20
	global_atomic_add v2, v1, v2, s[38:39] offset:256 sc0
